# attention (MLA and SWA): s_setprio 2 while a wave streams its fragment reads and MFMAs, back to 0 for the softmax VALU
# speedup vs baseline: 1.0001x; 1.0001x over previous
.LBB0_379:
.LBB0_380:
	v_add_u32_e32 v172, v103, v124
	ds_read_b128 v[140:143], v172
	ds_read_b128 v[144:147], v172 offset:2560
	ds_read_b128 v[148:151], v172 offset:5120
	ds_read_b128 v[152:155], v172 offset:7680
	s_setprio 2
	s_waitcnt lgkmcnt(3)
	v_mfma_f32_16x16x32_bf16 v[2:5], v[140:143], v[74:77], v[2:5]
	v_mfma_f32_16x16x32_bf16 v[6:9], v[140:143], v[78:81], v[6:9]
	s_waitcnt lgkmcnt(2)
	v_mfma_f32_16x16x32_bf16 v[10:13], v[144:147], v[74:77], v[10:13]
	v_mfma_f32_16x16x32_bf16 v[14:17], v[144:147], v[78:81], v[14:17]
	s_waitcnt lgkmcnt(1)
	v_mfma_f32_16x16x32_bf16 v[18:21], v[148:151], v[74:77], v[18:21]
	v_mfma_f32_16x16x32_bf16 v[22:25], v[148:151], v[78:81], v[22:25]
	s_waitcnt lgkmcnt(0)
	v_mfma_f32_16x16x32_bf16 v[26:29], v[152:155], v[74:77], v[26:29]
	v_mfma_f32_16x16x32_bf16 v[30:33], v[152:155], v[78:81], v[30:33]
	s_setprio 0
	ds_bpermute_b32 v166, v126, v87
	ds_bpermute_b32 v167, v126, v136
	s_waitcnt lgkmcnt(0)
	v_add_f32_e32 v87, v87, v166
	v_add_f32_e32 v136, v136, v167
	ds_bpermute_b32 v166, v85, v87
	ds_bpermute_b32 v167, v85, v136
	s_waitcnt lgkmcnt(0)
	v_add_f32_e32 v87, v87, v166
	v_add_f32_e32 v136, v136, v167
	s_barrier
	v_div_scale_f32 v34, s[8:9], v87, v87, 1.0
	v_rcp_f32_e32 v35, v34
	s_nop 0
	v_fma_f32 v36, -v34, v35, 1.0
	v_fmac_f32_e32 v35, v36, v35
	v_div_scale_f32 v36, vcc, 1.0, v87, 1.0
	v_mul_f32_e32 v37, v36, v35
	v_fma_f32 v38, -v34, v37, v36
	v_fmac_f32_e32 v37, v38, v35
	v_fma_f32 v34, -v34, v37, v36
	v_div_fmas_f32 v34, v34, v35, v37
	v_div_fixup_f32 v34, v34, v87, 1.0
	v_div_scale_f32 v42, s[8:9], v136, v136, 1.0
	v_rcp_f32_e32 v43, v42
	s_nop 0
	v_fma_f32 v44, -v42, v43, 1.0
	v_fmac_f32_e32 v43, v44, v43
	v_div_scale_f32 v44, vcc, 1.0, v136, 1.0
	v_mul_f32_e32 v45, v44, v43
	v_fma_f32 v46, -v42, v45, v44
	v_fmac_f32_e32 v45, v46, v43
	v_fma_f32 v42, -v42, v45, v44
	v_div_fmas_f32 v42, v42, v43, v45
	v_div_fixup_f32 v42, v42, v136, 1.0
	s_lshl_b32 s4, s88, 7
	s_add_u32 s4, s76, s4
	s_addc_u32 s5, s77, 0
	v_and_b32_e32 v138, 15, v162
	v_add_u32_e32 v138, v93, v138
	v_ashrrev_i32_e32 v139, 31, v138
	v_lshlrev_b64 v[138:139], 11, v[138:139]
	v_lshl_add_u64 v[138:139], s[4:5], 0, v[138:139]
	v_bfe_u32 v166, v162, 4, 2
	v_lshlrev_b32_e32 v166, 3, v166
	v_mov_b32_e32 v167, 0
	v_lshl_add_u64 v[138:139], v[138:139], 0, v[166:167]
	v_add_co_u32_e32 v166, vcc, 0x8000, v138
	s_nop 1
	v_addc_co_u32_e32 v167, vcc, 0, v139, vcc
	v_mul_f32_e32 v2, v2, v34
	v_mul_f32_e32 v3, v3, v34
	v_mul_f32_e32 v4, v4, v34
	v_mul_f32_e32 v5, v5, v34
	v_cvt_pk_bf16_f32 v168, v2, v3
	v_cvt_pk_bf16_f32 v169, v4, v5
	global_store_dwordx2 v[138:139], v[168:169], off
	v_mul_f32_e32 v6, v6, v42
	v_mul_f32_e32 v7, v7, v42
	v_mul_f32_e32 v8, v8, v42
	v_mul_f32_e32 v9, v9, v42
	v_cvt_pk_bf16_f32 v170, v6, v7
	v_cvt_pk_bf16_f32 v171, v8, v9
	global_store_dwordx2 v[166:167], v[170:171], off
	v_mul_f32_e32 v10, v10, v34
	v_mul_f32_e32 v11, v11, v34
	v_mul_f32_e32 v12, v12, v34
	v_mul_f32_e32 v13, v13, v34
	v_cvt_pk_bf16_f32 v168, v10, v11
	v_cvt_pk_bf16_f32 v169, v12, v13
	global_store_dwordx2 v[138:139], v[168:169], off offset:32
	v_mul_f32_e32 v14, v14, v42
	v_mul_f32_e32 v15, v15, v42
	v_mul_f32_e32 v16, v16, v42
	v_mul_f32_e32 v17, v17, v42
	v_cvt_pk_bf16_f32 v170, v14, v15
	v_cvt_pk_bf16_f32 v171, v16, v17
	global_store_dwordx2 v[166:167], v[170:171], off offset:32
	v_mul_f32_e32 v18, v18, v34
	v_mul_f32_e32 v19, v19, v34
	v_mul_f32_e32 v20, v20, v34
	v_mul_f32_e32 v21, v21, v34
	v_cvt_pk_bf16_f32 v168, v18, v19
	v_cvt_pk_bf16_f32 v169, v20, v21
	global_store_dwordx2 v[138:139], v[168:169], off offset:64
	v_mul_f32_e32 v22, v22, v42
	v_mul_f32_e32 v23, v23, v42
	v_mul_f32_e32 v24, v24, v42
	v_mul_f32_e32 v25, v25, v42
	v_cvt_pk_bf16_f32 v170, v22, v23
	v_cvt_pk_bf16_f32 v171, v24, v25
	global_store_dwordx2 v[166:167], v[170:171], off offset:64
	v_mul_f32_e32 v26, v26, v34
	v_mul_f32_e32 v27, v27, v34
	v_mul_f32_e32 v28, v28, v34
	v_mul_f32_e32 v29, v29, v34
	v_cvt_pk_bf16_f32 v168, v26, v27
	v_cvt_pk_bf16_f32 v169, v28, v29
	global_store_dwordx2 v[138:139], v[168:169], off offset:96
	v_mul_f32_e32 v30, v30, v42
	v_mul_f32_e32 v31, v31, v42
	v_mul_f32_e32 v32, v32, v42
	v_mul_f32_e32 v33, v33, v42
	v_cvt_pk_bf16_f32 v170, v30, v31
	v_cvt_pk_bf16_f32 v171, v32, v33
	global_store_dwordx2 v[166:167], v[170:171], off offset:96
	s_add_i32 s87, s87, s30
	s_cmpk_gt_i32 s87, 0x3ff
	s_cbranch_scc1 .LBB0_401

.Lw3_tile_go:
.Lw3_h0:
	s_mov_b32 s101, s10
	s_sub_i32 s99, s98, s101
	s_add_i32 s100, s99, 63
	s_cmp_lt_u32 s100, 222
	s_cbranch_scc0 .Lw3_h0_end
	v_mov_b32_e32 v173, v98
	v_add_u32_e32 v172, v103, v124
	s_add_i32 s4, s11, 0x5000
	ds_read_b128 v[140:143], v173
	ds_read_b128 v[144:147], v173 offset:1280
	ds_read_b128 v[148:151], v173 offset:64
	ds_read_b128 v[152:155], v173 offset:1344
	v_mov_b32_e32 v103, s4
	s_setprio 2
	s_waitcnt lgkmcnt(3)
	v_mfma_f32_16x16x32_bf16 v[34:37], v[140:143], v[50:53], v[128:131]
	v_mfma_f32_16x16x32_bf16 v[38:41], v[140:143], v[58:61], v[132:135]
	ds_read_b128 v[156:159], v172
	s_waitcnt lgkmcnt(3)
	v_mfma_f32_16x16x32_bf16 v[42:45], v[144:147], v[50:53], v[128:131]
	v_mfma_f32_16x16x32_bf16 v[46:49], v[144:147], v[58:61], v[132:135]
	ds_read_b128 v[140:143], v172 offset:2560
	s_waitcnt lgkmcnt(3)
	v_mfma_f32_16x16x32_bf16 v[34:37], v[148:151], v[54:57], v[34:37]
	v_mfma_f32_16x16x32_bf16 v[38:41], v[148:151], v[66:69], v[38:41]
	ds_read_b128 v[144:147], v172 offset:5120
	s_waitcnt lgkmcnt(3)
	v_mfma_f32_16x16x32_bf16 v[42:45], v[152:155], v[54:57], v[42:45]
	v_mfma_f32_16x16x32_bf16 v[46:49], v[152:155], v[66:69], v[46:49]
	ds_read_b128 v[148:151], v172 offset:7680
	s_waitcnt lgkmcnt(3)
	v_mfma_f32_16x16x32_bf16 v[2:5], v[156:159], v[74:77], v[2:5]
	v_mfma_f32_16x16x32_bf16 v[6:9], v[156:159], v[78:81], v[6:9]
	s_waitcnt lgkmcnt(2)
	v_mfma_f32_16x16x32_bf16 v[10:13], v[140:143], v[74:77], v[10:13]
	v_mfma_f32_16x16x32_bf16 v[14:17], v[140:143], v[78:81], v[14:17]
	s_waitcnt lgkmcnt(1)
	v_mfma_f32_16x16x32_bf16 v[18:21], v[144:147], v[74:77], v[18:21]
	v_mfma_f32_16x16x32_bf16 v[22:25], v[144:147], v[78:81], v[22:25]
	s_waitcnt lgkmcnt(0)
	v_mfma_f32_16x16x32_bf16 v[26:29], v[148:151], v[74:77], v[26:29]
	v_mfma_f32_16x16x32_bf16 v[30:33], v[148:151], v[78:81], v[30:33]
	s_setprio 0
	s_cmp_lt_i32 s99, 31
	s_cbranch_scc1 .Lw3_h0_mask
	s_cmp_ge_i32 s99, 97
	s_cbranch_scc1 .Lw3_h0_wmask

.Lw3_h0_end:
.Lw3_h1:
	s_add_i32 s101, s10, 32
	s_sub_i32 s99, s98, s101
	s_add_i32 s100, s99, 63
	s_cmp_lt_u32 s100, 222
	s_cbranch_scc0 .Lw3_h1_end
	v_add_u32_e32 v173, 0x1400, v98
	v_add_u32_e32 v172, v103, v124
	s_add_i32 s4, s11, 0x5040
	ds_read_b128 v[140:143], v173
	ds_read_b128 v[144:147], v173 offset:1280
	ds_read_b128 v[148:151], v173 offset:64
	ds_read_b128 v[152:155], v173 offset:1344
	v_mov_b32_e32 v103, s4
	s_setprio 2
	s_waitcnt lgkmcnt(3)
	v_mfma_f32_16x16x32_bf16 v[34:37], v[140:143], v[50:53], v[128:131]
	v_mfma_f32_16x16x32_bf16 v[38:41], v[140:143], v[58:61], v[132:135]
	ds_read_b128 v[156:159], v172
	s_waitcnt lgkmcnt(3)
	v_mfma_f32_16x16x32_bf16 v[42:45], v[144:147], v[50:53], v[128:131]
	v_mfma_f32_16x16x32_bf16 v[46:49], v[144:147], v[58:61], v[132:135]
	ds_read_b128 v[140:143], v172 offset:2560
	s_waitcnt lgkmcnt(3)
	v_mfma_f32_16x16x32_bf16 v[34:37], v[148:151], v[54:57], v[34:37]
	v_mfma_f32_16x16x32_bf16 v[38:41], v[148:151], v[66:69], v[38:41]
	ds_read_b128 v[144:147], v172 offset:5120
	s_waitcnt lgkmcnt(3)
	v_mfma_f32_16x16x32_bf16 v[42:45], v[152:155], v[54:57], v[42:45]
	v_mfma_f32_16x16x32_bf16 v[46:49], v[152:155], v[66:69], v[46:49]
	ds_read_b128 v[148:151], v172 offset:7680
	s_waitcnt lgkmcnt(3)
	v_mfma_f32_16x16x32_bf16 v[2:5], v[156:159], v[74:77], v[2:5]
	v_mfma_f32_16x16x32_bf16 v[6:9], v[156:159], v[78:81], v[6:9]
	s_waitcnt lgkmcnt(2)
	v_mfma_f32_16x16x32_bf16 v[10:13], v[140:143], v[74:77], v[10:13]
	v_mfma_f32_16x16x32_bf16 v[14:17], v[140:143], v[78:81], v[14:17]
	s_waitcnt lgkmcnt(1)
	v_mfma_f32_16x16x32_bf16 v[18:21], v[144:147], v[74:77], v[18:21]
	v_mfma_f32_16x16x32_bf16 v[22:25], v[144:147], v[78:81], v[22:25]
	s_waitcnt lgkmcnt(0)
	v_mfma_f32_16x16x32_bf16 v[26:29], v[148:151], v[74:77], v[26:29]
	v_mfma_f32_16x16x32_bf16 v[30:33], v[148:151], v[78:81], v[30:33]
	s_setprio 0
	s_cmp_lt_i32 s99, 31
	s_cbranch_scc1 .Lw3_h1_mask
	s_cmp_ge_i32 s99, 97
	s_cbranch_scc1 .Lw3_h1_wmask

.LBB0_761:
	v_add_u32_e32 v238, v209, v200
	ds_read_b128 v[218:221], v238
	ds_read_b128 v[222:225], v238 offset:2560
	ds_read_b128 v[226:229], v238 offset:5120
	ds_read_b128 v[230:233], v238 offset:7680
	s_setprio 2
	s_waitcnt lgkmcnt(3)
	v_mfma_f32_16x16x32_bf16 v[2:5], v[218:221], v[150:153], v[2:5]
	v_mfma_f32_16x16x32_bf16 v[6:9], v[218:221], v[154:157], v[6:9]
	ds_read_b128 v[234:237], v238 offset:10240
	s_waitcnt lgkmcnt(3)
	v_mfma_f32_16x16x32_bf16 v[10:13], v[222:225], v[150:153], v[10:13]
	v_mfma_f32_16x16x32_bf16 v[14:17], v[222:225], v[154:157], v[14:17]
	ds_read_b128 v[218:221], v238 offset:12800
	s_waitcnt lgkmcnt(3)
	v_mfma_f32_16x16x32_bf16 v[18:21], v[226:229], v[150:153], v[18:21]
	v_mfma_f32_16x16x32_bf16 v[22:25], v[226:229], v[154:157], v[22:25]
	ds_read_b128 v[222:225], v238 offset:15360
	s_waitcnt lgkmcnt(3)
	v_mfma_f32_16x16x32_bf16 v[26:29], v[230:233], v[150:153], v[26:29]
	v_mfma_f32_16x16x32_bf16 v[30:33], v[230:233], v[154:157], v[30:33]
	ds_read_b128 v[226:229], v238 offset:17920
	s_waitcnt lgkmcnt(3)
	v_mfma_f32_16x16x32_bf16 v[34:37], v[234:237], v[150:153], v[34:37]
	v_mfma_f32_16x16x32_bf16 v[38:41], v[234:237], v[154:157], v[38:41]
	s_waitcnt lgkmcnt(2)
	v_mfma_f32_16x16x32_bf16 v[42:45], v[218:221], v[150:153], v[42:45]
	v_mfma_f32_16x16x32_bf16 v[46:49], v[218:221], v[154:157], v[46:49]
	s_waitcnt lgkmcnt(1)
	v_mfma_f32_16x16x32_bf16 v[50:53], v[222:225], v[150:153], v[50:53]
	v_mfma_f32_16x16x32_bf16 v[54:57], v[222:225], v[154:157], v[54:57]
	s_waitcnt lgkmcnt(0)
	v_mfma_f32_16x16x32_bf16 v[58:61], v[226:229], v[150:153], v[58:61]
	v_mfma_f32_16x16x32_bf16 v[62:65], v[226:229], v[154:157], v[62:65]
	s_setprio 0
	ds_bpermute_b32 v245, v208, v199
	ds_bpermute_b32 v247, v208, v203
	s_waitcnt lgkmcnt(0)
	v_add_f32_e32 v199, v199, v245
	v_add_f32_e32 v203, v203, v247
	ds_bpermute_b32 v245, v198, v199
	ds_bpermute_b32 v247, v198, v203
	s_waitcnt lgkmcnt(0)
	v_add_f32_e32 v199, v199, v245
	v_add_f32_e32 v203, v203, v247
	s_barrier
	v_div_scale_f32 v66, s[6:7], v199, v199, 1.0
	v_rcp_f32_e32 v67, v66
	s_nop 0
	v_fma_f32 v68, -v66, v67, 1.0
	v_fmac_f32_e32 v67, v68, v67
	v_div_scale_f32 v68, vcc, 1.0, v199, 1.0
	v_mul_f32_e32 v69, v68, v67
	v_fma_f32 v70, -v66, v69, v68
	v_fmac_f32_e32 v69, v70, v67
	v_fma_f32 v66, -v66, v69, v68
	v_div_fmas_f32 v66, v66, v67, v69
	v_div_fixup_f32 v66, v66, v199, 1.0
	v_div_scale_f32 v74, s[6:7], v203, v203, 1.0
	v_rcp_f32_e32 v75, v74
	s_nop 0
	v_fma_f32 v76, -v74, v75, 1.0
	v_fmac_f32_e32 v75, v76, v75
	v_div_scale_f32 v76, vcc, 1.0, v203, 1.0
	v_mul_f32_e32 v77, v76, v75
	v_fma_f32 v78, -v74, v77, v76
	v_fmac_f32_e32 v77, v78, v75
	v_fma_f32 v74, -v74, v77, v76
	v_div_fmas_f32 v74, v74, v75, v77
	v_div_fixup_f32 v74, v74, v203, 1.0
	s_lshl_b32 s4, s86, 8
	s_add_u32 s4, s75, s4
	s_addc_u32 s5, s76, 0
	v_ashrrev_i32_e32 v159, 31, v158
	v_lshlrev_b64 v[238:239], 11, v[158:159]
	v_lshl_add_u64 v[238:239], s[4:5], 0, v[238:239]
	v_bfe_u32 v0, v162, 4, 2
	v_lshlrev_b32_e32 v0, 3, v0
	v_lshl_add_u64 v[238:239], v[238:239], 0, v[0:1]
	v_add_co_u32_e32 v244, vcc, 0x8000, v238
	s_nop 1
	v_addc_co_u32_e32 v245, vcc, 0, v239, vcc
	v_mul_f32_e32 v2, v2, v66
	v_mul_f32_e32 v3, v3, v66
	v_mul_f32_e32 v4, v4, v66
	v_mul_f32_e32 v5, v5, v66
	v_cvt_pk_bf16_f32 v240, v2, v3
	v_cvt_pk_bf16_f32 v241, v4, v5
	global_store_dwordx2 v[238:239], v[240:241], off
	v_mul_f32_e32 v6, v6, v74
	v_mul_f32_e32 v7, v7, v74
	v_mul_f32_e32 v8, v8, v74
	v_mul_f32_e32 v9, v9, v74
	v_cvt_pk_bf16_f32 v242, v6, v7
	v_cvt_pk_bf16_f32 v243, v8, v9
	global_store_dwordx2 v[244:245], v[242:243], off
	v_mul_f32_e32 v10, v10, v66
	v_mul_f32_e32 v11, v11, v66
	v_mul_f32_e32 v12, v12, v66
	v_mul_f32_e32 v13, v13, v66
	v_cvt_pk_bf16_f32 v240, v10, v11
	v_cvt_pk_bf16_f32 v241, v12, v13
	global_store_dwordx2 v[238:239], v[240:241], off offset:32
	v_mul_f32_e32 v14, v14, v74
	v_mul_f32_e32 v15, v15, v74
	v_mul_f32_e32 v16, v16, v74
	v_mul_f32_e32 v17, v17, v74
	v_cvt_pk_bf16_f32 v242, v14, v15
	v_cvt_pk_bf16_f32 v243, v16, v17
	global_store_dwordx2 v[244:245], v[242:243], off offset:32
	v_mul_f32_e32 v18, v18, v66
	v_mul_f32_e32 v19, v19, v66
	v_mul_f32_e32 v20, v20, v66
	v_mul_f32_e32 v21, v21, v66
	v_cvt_pk_bf16_f32 v240, v18, v19
	v_cvt_pk_bf16_f32 v241, v20, v21
	global_store_dwordx2 v[238:239], v[240:241], off offset:64
	v_mul_f32_e32 v22, v22, v74
	v_mul_f32_e32 v23, v23, v74
	v_mul_f32_e32 v24, v24, v74
	v_mul_f32_e32 v25, v25, v74
	v_cvt_pk_bf16_f32 v242, v22, v23
	v_cvt_pk_bf16_f32 v243, v24, v25
	global_store_dwordx2 v[244:245], v[242:243], off offset:64
	v_mul_f32_e32 v26, v26, v66
	v_mul_f32_e32 v27, v27, v66
	v_mul_f32_e32 v28, v28, v66
	v_mul_f32_e32 v29, v29, v66
	v_cvt_pk_bf16_f32 v240, v26, v27
	v_cvt_pk_bf16_f32 v241, v28, v29
	global_store_dwordx2 v[238:239], v[240:241], off offset:96
	v_mul_f32_e32 v30, v30, v74
	v_mul_f32_e32 v31, v31, v74
	v_mul_f32_e32 v32, v32, v74
	v_mul_f32_e32 v33, v33, v74
	v_cvt_pk_bf16_f32 v242, v30, v31
	v_cvt_pk_bf16_f32 v243, v32, v33
	global_store_dwordx2 v[244:245], v[242:243], off offset:96
	v_mul_f32_e32 v34, v34, v66
	v_mul_f32_e32 v35, v35, v66
	v_mul_f32_e32 v36, v36, v66
	v_mul_f32_e32 v37, v37, v66
	v_cvt_pk_bf16_f32 v240, v34, v35
	v_cvt_pk_bf16_f32 v241, v36, v37
	global_store_dwordx2 v[238:239], v[240:241], off offset:128
	v_mul_f32_e32 v38, v38, v74
	v_mul_f32_e32 v39, v39, v74
	v_mul_f32_e32 v40, v40, v74
	v_mul_f32_e32 v41, v41, v74
	v_cvt_pk_bf16_f32 v242, v38, v39
	v_cvt_pk_bf16_f32 v243, v40, v41
	global_store_dwordx2 v[244:245], v[242:243], off offset:128
	v_mul_f32_e32 v42, v42, v66
	v_mul_f32_e32 v43, v43, v66
	v_mul_f32_e32 v44, v44, v66
	v_mul_f32_e32 v45, v45, v66
	v_cvt_pk_bf16_f32 v240, v42, v43
	v_cvt_pk_bf16_f32 v241, v44, v45
	global_store_dwordx2 v[238:239], v[240:241], off offset:160
	v_mul_f32_e32 v46, v46, v74
	v_mul_f32_e32 v47, v47, v74
	v_mul_f32_e32 v48, v48, v74
	v_mul_f32_e32 v49, v49, v74
	v_cvt_pk_bf16_f32 v242, v46, v47
	v_cvt_pk_bf16_f32 v243, v48, v49
	global_store_dwordx2 v[244:245], v[242:243], off offset:160
	v_mul_f32_e32 v50, v50, v66
	v_mul_f32_e32 v51, v51, v66
	v_mul_f32_e32 v52, v52, v66
	v_mul_f32_e32 v53, v53, v66
	v_cvt_pk_bf16_f32 v240, v50, v51
	v_cvt_pk_bf16_f32 v241, v52, v53
	global_store_dwordx2 v[238:239], v[240:241], off offset:192
	v_mul_f32_e32 v54, v54, v74
	v_mul_f32_e32 v55, v55, v74
	v_mul_f32_e32 v56, v56, v74
	v_mul_f32_e32 v57, v57, v74
	v_cvt_pk_bf16_f32 v242, v54, v55
	v_cvt_pk_bf16_f32 v243, v56, v57
	global_store_dwordx2 v[244:245], v[242:243], off offset:192
	v_mul_f32_e32 v58, v58, v66
	v_mul_f32_e32 v59, v59, v66
	v_mul_f32_e32 v60, v60, v66
	v_mul_f32_e32 v61, v61, v66
	v_cvt_pk_bf16_f32 v240, v58, v59
	v_cvt_pk_bf16_f32 v241, v60, v61
	global_store_dwordx2 v[238:239], v[240:241], off offset:224
	v_mul_f32_e32 v62, v62, v74
	v_mul_f32_e32 v63, v63, v74
	v_mul_f32_e32 v64, v64, v74
	v_mul_f32_e32 v65, v65, v74
	v_cvt_pk_bf16_f32 v242, v62, v63
	v_cvt_pk_bf16_f32 v243, v64, v65
	global_store_dwordx2 v[244:245], v[242:243], off offset:224

.Lv3_h0:
	s_mov_b32 s91, s54
	s_add_i32 s13, s12, 63
	s_cmp_le_i32 s91, s13
	s_cbranch_scc0 .Lv3_h0_end
	v_mov_b32_e32 v205, v204
	v_add_u32_e32 v238, v209, v200
	s_add_i32 s4, s89, 0xd000
	ds_read_b128 v[218:221], v205
	ds_read_b128 v[222:225], v205 offset:3328
	ds_read_b128 v[226:229], v205 offset:64
	ds_read_b128 v[230:233], v205 offset:3392
	v_mov_b32_e32 v209, s4
	s_setprio 2
	s_waitcnt lgkmcnt(3)
	v_mfma_f32_16x16x32_bf16 v[66:69], v[218:221], v[82:85], v[210:213]
	v_mfma_f32_16x16x32_bf16 v[70:73], v[218:221], v[106:109], v[214:217]
	ds_read_b128 v[234:237], v205 offset:128
	s_waitcnt lgkmcnt(3)
	v_mfma_f32_16x16x32_bf16 v[74:77], v[222:225], v[82:85], v[210:213]
	v_mfma_f32_16x16x32_bf16 v[78:81], v[222:225], v[106:109], v[214:217]
	ds_read_b128 v[218:221], v205 offset:3456
	s_waitcnt lgkmcnt(3)
	v_mfma_f32_16x16x32_bf16 v[66:69], v[226:229], v[86:89], v[66:69]
	v_mfma_f32_16x16x32_bf16 v[70:73], v[226:229], v[110:113], v[70:73]
	ds_read_b128 v[222:225], v205 offset:192
	s_waitcnt lgkmcnt(3)
	v_mfma_f32_16x16x32_bf16 v[74:77], v[230:233], v[86:89], v[74:77]
	v_mfma_f32_16x16x32_bf16 v[78:81], v[230:233], v[110:113], v[78:81]
	ds_read_b128 v[226:229], v205 offset:3520
	s_waitcnt lgkmcnt(3)
	v_mfma_f32_16x16x32_bf16 v[66:69], v[234:237], v[90:93], v[66:69]
	v_mfma_f32_16x16x32_bf16 v[70:73], v[234:237], v[114:117], v[70:73]
	ds_read_b128 v[230:233], v205 offset:256
	s_waitcnt lgkmcnt(3)
	v_mfma_f32_16x16x32_bf16 v[74:77], v[218:221], v[90:93], v[74:77]
	v_mfma_f32_16x16x32_bf16 v[78:81], v[218:221], v[114:117], v[78:81]
	ds_read_b128 v[234:237], v205 offset:3584
	s_waitcnt lgkmcnt(3)
	v_mfma_f32_16x16x32_bf16 v[66:69], v[222:225], v[94:97], v[66:69]
	v_mfma_f32_16x16x32_bf16 v[70:73], v[222:225], v[118:121], v[70:73]
	ds_read_b128 v[218:221], v205 offset:320
	s_waitcnt lgkmcnt(3)
	v_mfma_f32_16x16x32_bf16 v[74:77], v[226:229], v[94:97], v[74:77]
	v_mfma_f32_16x16x32_bf16 v[78:81], v[226:229], v[118:121], v[78:81]
	ds_read_b128 v[222:225], v205 offset:3648
	s_waitcnt lgkmcnt(3)
	v_mfma_f32_16x16x32_bf16 v[66:69], v[230:233], v[98:101], v[66:69]
	v_mfma_f32_16x16x32_bf16 v[70:73], v[230:233], v[122:125], v[70:73]
	ds_read_b128 v[226:229], v238
	s_waitcnt lgkmcnt(3)
	v_mfma_f32_16x16x32_bf16 v[74:77], v[234:237], v[98:101], v[74:77]
	v_mfma_f32_16x16x32_bf16 v[78:81], v[234:237], v[122:125], v[78:81]
	ds_read_b128 v[230:233], v238 offset:2560
	s_waitcnt lgkmcnt(3)
	v_mfma_f32_16x16x32_bf16 v[66:69], v[218:221], v[102:105], v[66:69]
	v_mfma_f32_16x16x32_bf16 v[70:73], v[218:221], v[126:129], v[70:73]
	ds_read_b128 v[234:237], v238 offset:5120
	s_waitcnt lgkmcnt(3)
	v_mfma_f32_16x16x32_bf16 v[74:77], v[222:225], v[102:105], v[74:77]
	v_mfma_f32_16x16x32_bf16 v[78:81], v[222:225], v[126:129], v[78:81]
	ds_read_b128 v[218:221], v238 offset:7680
	s_waitcnt lgkmcnt(3)
	v_mfma_f32_16x16x32_bf16 v[2:5], v[226:229], v[150:153], v[2:5]
	v_mfma_f32_16x16x32_bf16 v[6:9], v[226:229], v[154:157], v[6:9]
	ds_read_b128 v[222:225], v238 offset:10240
	s_waitcnt lgkmcnt(3)
	v_mfma_f32_16x16x32_bf16 v[10:13], v[230:233], v[150:153], v[10:13]
	v_mfma_f32_16x16x32_bf16 v[14:17], v[230:233], v[154:157], v[14:17]
	ds_read_b128 v[226:229], v238 offset:12800
	s_waitcnt lgkmcnt(3)
	v_mfma_f32_16x16x32_bf16 v[18:21], v[234:237], v[150:153], v[18:21]
	v_mfma_f32_16x16x32_bf16 v[22:25], v[234:237], v[154:157], v[22:25]
	ds_read_b128 v[230:233], v238 offset:15360
	s_waitcnt lgkmcnt(3)
	v_mfma_f32_16x16x32_bf16 v[26:29], v[218:221], v[150:153], v[26:29]
	v_mfma_f32_16x16x32_bf16 v[30:33], v[218:221], v[154:157], v[30:33]
	ds_read_b128 v[234:237], v238 offset:17920
	s_waitcnt lgkmcnt(3)
	v_mfma_f32_16x16x32_bf16 v[34:37], v[222:225], v[150:153], v[34:37]
	v_mfma_f32_16x16x32_bf16 v[38:41], v[222:225], v[154:157], v[38:41]
	s_waitcnt lgkmcnt(2)
	v_mfma_f32_16x16x32_bf16 v[42:45], v[226:229], v[150:153], v[42:45]
	v_mfma_f32_16x16x32_bf16 v[46:49], v[226:229], v[154:157], v[46:49]
	s_waitcnt lgkmcnt(1)
	v_mfma_f32_16x16x32_bf16 v[50:53], v[230:233], v[150:153], v[50:53]
	v_mfma_f32_16x16x32_bf16 v[54:57], v[230:233], v[154:157], v[54:57]
	s_waitcnt lgkmcnt(0)
	v_mfma_f32_16x16x32_bf16 v[58:61], v[234:237], v[150:153], v[58:61]
	v_mfma_f32_16x16x32_bf16 v[62:65], v[234:237], v[154:157], v[62:65]
	s_setprio 0
	s_add_i32 s13, s91, 31
	s_cmp_gt_i32 s13, s12
	s_cbranch_scc1 .Lv3_h0_mask

.Lv3_h0_end:
.Lv3_h1:
	s_add_i32 s91, s54, 32
	s_add_i32 s13, s12, 63
	s_cmp_le_i32 s91, s13
	s_cbranch_scc0 .Lv3_h1_end
	v_add_u32_e32 v205, 0x3400, v204
	v_add_u32_e32 v238, v209, v200
	s_add_i32 s4, s89, 0xd040
	ds_read_b128 v[218:221], v205
	ds_read_b128 v[222:225], v205 offset:3328
	ds_read_b128 v[226:229], v205 offset:64
	ds_read_b128 v[230:233], v205 offset:3392
	v_mov_b32_e32 v209, s4
	s_setprio 2
	s_waitcnt lgkmcnt(3)
	v_mfma_f32_16x16x32_bf16 v[66:69], v[218:221], v[82:85], v[210:213]
	v_mfma_f32_16x16x32_bf16 v[70:73], v[218:221], v[106:109], v[214:217]
	ds_read_b128 v[234:237], v205 offset:128
	s_waitcnt lgkmcnt(3)
	v_mfma_f32_16x16x32_bf16 v[74:77], v[222:225], v[82:85], v[210:213]
	v_mfma_f32_16x16x32_bf16 v[78:81], v[222:225], v[106:109], v[214:217]
	ds_read_b128 v[218:221], v205 offset:3456
	s_waitcnt lgkmcnt(3)
	v_mfma_f32_16x16x32_bf16 v[66:69], v[226:229], v[86:89], v[66:69]
	v_mfma_f32_16x16x32_bf16 v[70:73], v[226:229], v[110:113], v[70:73]
	ds_read_b128 v[222:225], v205 offset:192
	s_waitcnt lgkmcnt(3)
	v_mfma_f32_16x16x32_bf16 v[74:77], v[230:233], v[86:89], v[74:77]
	v_mfma_f32_16x16x32_bf16 v[78:81], v[230:233], v[110:113], v[78:81]
	ds_read_b128 v[226:229], v205 offset:3520
	s_waitcnt lgkmcnt(3)
	v_mfma_f32_16x16x32_bf16 v[66:69], v[234:237], v[90:93], v[66:69]
	v_mfma_f32_16x16x32_bf16 v[70:73], v[234:237], v[114:117], v[70:73]
	ds_read_b128 v[230:233], v205 offset:256
	s_waitcnt lgkmcnt(3)
	v_mfma_f32_16x16x32_bf16 v[74:77], v[218:221], v[90:93], v[74:77]
	v_mfma_f32_16x16x32_bf16 v[78:81], v[218:221], v[114:117], v[78:81]
	ds_read_b128 v[234:237], v205 offset:3584
	s_waitcnt lgkmcnt(3)
	v_mfma_f32_16x16x32_bf16 v[66:69], v[222:225], v[94:97], v[66:69]
	v_mfma_f32_16x16x32_bf16 v[70:73], v[222:225], v[118:121], v[70:73]
	ds_read_b128 v[218:221], v205 offset:320
	s_waitcnt lgkmcnt(3)
	v_mfma_f32_16x16x32_bf16 v[74:77], v[226:229], v[94:97], v[74:77]
	v_mfma_f32_16x16x32_bf16 v[78:81], v[226:229], v[118:121], v[78:81]
	ds_read_b128 v[222:225], v205 offset:3648
	s_waitcnt lgkmcnt(3)
	v_mfma_f32_16x16x32_bf16 v[66:69], v[230:233], v[98:101], v[66:69]
	v_mfma_f32_16x16x32_bf16 v[70:73], v[230:233], v[122:125], v[70:73]
	ds_read_b128 v[226:229], v238
	s_waitcnt lgkmcnt(3)
	v_mfma_f32_16x16x32_bf16 v[74:77], v[234:237], v[98:101], v[74:77]
	v_mfma_f32_16x16x32_bf16 v[78:81], v[234:237], v[122:125], v[78:81]
	ds_read_b128 v[230:233], v238 offset:2560
	s_waitcnt lgkmcnt(3)
	v_mfma_f32_16x16x32_bf16 v[66:69], v[218:221], v[102:105], v[66:69]
	v_mfma_f32_16x16x32_bf16 v[70:73], v[218:221], v[126:129], v[70:73]
	ds_read_b128 v[234:237], v238 offset:5120
	s_waitcnt lgkmcnt(3)
	v_mfma_f32_16x16x32_bf16 v[74:77], v[222:225], v[102:105], v[74:77]
	v_mfma_f32_16x16x32_bf16 v[78:81], v[222:225], v[126:129], v[78:81]
	ds_read_b128 v[218:221], v238 offset:7680
	s_waitcnt lgkmcnt(3)
	v_mfma_f32_16x16x32_bf16 v[2:5], v[226:229], v[150:153], v[2:5]
	v_mfma_f32_16x16x32_bf16 v[6:9], v[226:229], v[154:157], v[6:9]
	ds_read_b128 v[222:225], v238 offset:10240
	s_waitcnt lgkmcnt(3)
	v_mfma_f32_16x16x32_bf16 v[10:13], v[230:233], v[150:153], v[10:13]
	v_mfma_f32_16x16x32_bf16 v[14:17], v[230:233], v[154:157], v[14:17]
	ds_read_b128 v[226:229], v238 offset:12800
	s_waitcnt lgkmcnt(3)
	v_mfma_f32_16x16x32_bf16 v[18:21], v[234:237], v[150:153], v[18:21]
	v_mfma_f32_16x16x32_bf16 v[22:25], v[234:237], v[154:157], v[22:25]
	ds_read_b128 v[230:233], v238 offset:15360
	s_waitcnt lgkmcnt(3)
	v_mfma_f32_16x16x32_bf16 v[26:29], v[218:221], v[150:153], v[26:29]
	v_mfma_f32_16x16x32_bf16 v[30:33], v[218:221], v[154:157], v[30:33]
	ds_read_b128 v[234:237], v238 offset:17920
	s_waitcnt lgkmcnt(3)
	v_mfma_f32_16x16x32_bf16 v[34:37], v[222:225], v[150:153], v[34:37]
	v_mfma_f32_16x16x32_bf16 v[38:41], v[222:225], v[154:157], v[38:41]
	s_waitcnt lgkmcnt(2)
	v_mfma_f32_16x16x32_bf16 v[42:45], v[226:229], v[150:153], v[42:45]
	v_mfma_f32_16x16x32_bf16 v[46:49], v[226:229], v[154:157], v[46:49]
	s_waitcnt lgkmcnt(1)
	v_mfma_f32_16x16x32_bf16 v[50:53], v[230:233], v[150:153], v[50:53]
	v_mfma_f32_16x16x32_bf16 v[54:57], v[230:233], v[154:157], v[54:57]
	s_waitcnt lgkmcnt(0)
	v_mfma_f32_16x16x32_bf16 v[58:61], v[234:237], v[150:153], v[58:61]
	v_mfma_f32_16x16x32_bf16 v[62:65], v[234:237], v[154:157], v[62:65]
	s_setprio 0
	s_add_i32 s13, s91, 31
	s_cmp_gt_i32 s13, s12
	s_cbranch_scc1 .Lv3_h1_mask
